# attention epilogue subln weight loads hoisted, kw wait relaxed, K/V prefetch flat->global, on top of step4 rewrite + prefetch
# speedup vs baseline: 1.0053x; 1.0053x over previous
; __device__ __forceinline__ void attn_unit(const Args& c, int l, int b, int h, int qb, float lam, float lam_init, LAS unsigned char* lds) {
;     ...
;     float l0 = lrow[0], l1 = lrow[1];
;     l0 += __shfl_xor(l0, 16); l0 += __shfl_xor(l0, 32); l1 += __shfl_xor(l1, 16); l1 += __shfl_xor(l1, 32);
;     const float i0 = 1.0f / l0, i1 = lam / l1;
;     float ss = 0.f;
; #pragma unroll
;     for (int vb = 0; vb < 8; ++vb)
; #pragma unroll
;         for (int e = 0; e < 4; ++e) { const float o = O[0][vb][e] * i0 - O[1][vb][e] * i1; O[0][vb][e] = o; ss += o * o; }
;     ss += __shfl_xor(ss, 16); ss += __shfl_xor(ss, 32);
;     const float rstd = rsqrtf(ss * (1.f / 128.f) + 1e-6f) * (1.0f - lam_init);
.LBB0_239:
	ds_bpermute_b32 v0, v205, v147
	v_readlane_b32 s6, v250, 42
	v_readlane_b32 s7, v250, 43
	s_lshl_b64 s[6:7], s[6:7], 2
	s_waitcnt vmcnt(0)
	v_lshlrev_b64 v[70:71], 12, v[184:185]
	s_waitcnt lgkmcnt(0)
	v_add_f32_e32 v0, v147, v0
	ds_bpermute_b32 v50, v206, v0
	v_lshl_add_u64 v[70:71], s[38:39], 0, v[70:71]
	s_mov_b32 s5, s15
	v_lshl_add_u64 v[70:71], v[70:71], 0, s[4:5]
	s_mov_b64 s[4:5], 0x18800800
	s_waitcnt lgkmcnt(0)
	v_add_f32_e32 v0, v0, v50
	ds_bpermute_b32 v50, v205, v146
	v_readlane_b32 s39, v253, 51
	s_waitcnt lgkmcnt(0)
	v_add_f32_e32 v50, v146, v50
	ds_bpermute_b32 v51, v206, v50
	s_waitcnt lgkmcnt(0)
	v_add_f32_e32 v50, v50, v51
	v_div_scale_f32 v51, s[2:3], v0, v0, 1.0
	v_rcp_f32_e32 v52, v51
	s_nop 0
	v_fma_f32 v53, -v51, v52, 1.0
	v_fmac_f32_e32 v52, v53, v52
	v_div_scale_f32 v53, vcc, 1.0, v0, 1.0
	v_mul_f32_e32 v54, v53, v52
	v_fma_f32 v55, -v51, v54, v53
	v_fmac_f32_e32 v54, v55, v52
	v_fma_f32 v51, -v51, v54, v53
	v_div_fmas_f32 v51, v51, v52, v54
	v_div_fixup_f32 v54, v51, v0, 1.0
	v_div_scale_f32 v0, s[2:3], v50, v50, v207
	v_rcp_f32_e32 v51, v0
	s_load_dwordx2 s[2:3], s[24:25], 0xe0
	v_fma_f32 v52, -v0, v51, 1.0
	v_fmac_f32_e32 v51, v52, v51
	v_div_scale_f32 v52, vcc, v207, v50, v207
	v_mul_f32_e32 v53, v52, v51
	v_fma_f32 v55, -v0, v53, v52
	v_fmac_f32_e32 v53, v55, v51
	v_fma_f32 v0, -v0, v53, v52
	v_div_fmas_f32 v0, v0, v51, v53
	v_div_fixup_f32 v56, v0, v50, v207
	v_pk_mul_f32 v[50:51], v[106:107], v[56:57] op_sel_hi:[1,0]
	s_waitcnt lgkmcnt(0)
	s_add_u32 s2, s2, s6
	v_pk_fma_f32 v[52:53], v[110:111], v[54:55], v[50:51] op_sel_hi:[1,0,1] neg_lo:[0,0,1] neg_hi:[0,0,1]
	v_pk_mul_f32 v[50:51], v[108:109], v[56:57] op_sel_hi:[1,0]
	s_addc_u32 s3, s3, s7
	v_pk_fma_f32 v[50:51], v[112:113], v[54:55], v[50:51] op_sel_hi:[1,0,1] neg_lo:[0,0,1] neg_hi:[0,0,1]
	v_lshlrev_b32_e32 v55, 2, v208
	v_pk_mul_f32 v[44:45], v[44:45], v[56:57] op_sel_hi:[1,0]
	v_pk_mul_f32 v[42:43], v[42:43], v[56:57] op_sel_hi:[1,0]
	v_pk_fma_f32 v[48:49], v[48:49], v[54:55], v[44:45] op_sel_hi:[1,0,1] neg_lo:[0,0,1] neg_hi:[0,0,1]
	v_pk_fma_f32 v[74:75], v[46:47], v[54:55], v[42:43] op_sel_hi:[1,0,1] neg_lo:[0,0,1] neg_hi:[0,0,1]
	global_load_dwordx4 v[44:47], v55, s[2:3]
	global_load_dwordx4 v[152:155], v55, s[2:3] offset:64
	global_load_dwordx4 v[156:159], v55, s[2:3] offset:128
	global_load_dwordx4 v[160:163], v55, s[2:3] offset:192
	global_load_dwordx4 v[164:167], v55, s[2:3] offset:256
	global_load_dwordx4 v[168:171], v55, s[2:3] offset:320
	global_load_dwordx4 v[172:175], v55, s[2:3] offset:384
	global_load_dwordx4 v[180:183], v55, s[2:3] offset:448
	v_pk_mul_f32 v[76:77], v[74:75], v[74:75]
	v_lshlrev_b32_e32 v0, 1, v208
	v_pk_mul_f32 v[72:73], v[48:49], v[48:49]
	v_lshl_add_u64 v[70:71], v[70:71], 0, v[0:1]
	v_pk_mul_f32 v[34:35], v[34:35], v[56:57] op_sel_hi:[1,0]
	v_add_f32_e32 v0, v76, v77
	v_pk_fma_f32 v[34:35], v[38:39], v[54:55], v[34:35] op_sel_hi:[1,0,1] neg_lo:[0,0,1] neg_hi:[0,0,1]
	v_add_f32_e32 v0, v72, v0
	v_pk_mul_f32 v[36:37], v[36:37], v[56:57] op_sel_hi:[1,0]
	v_pk_mul_f32 v[38:39], v[34:35], v[34:35]
	v_add_f32_e32 v0, v73, v0
	v_pk_fma_f32 v[36:37], v[40:41], v[54:55], v[36:37] op_sel_hi:[1,0,1] neg_lo:[0,0,1] neg_hi:[0,0,1]
	v_add_f32_e32 v0, v38, v0
	v_pk_mul_f32 v[40:41], v[36:37], v[36:37]
	v_pk_mul_f32 v[26:27], v[26:27], v[56:57] op_sel_hi:[1,0]
	v_add_f32_e32 v0, v39, v0
	v_pk_fma_f32 v[26:27], v[30:31], v[54:55], v[26:27] op_sel_hi:[1,0,1] neg_lo:[0,0,1] neg_hi:[0,0,1]
	v_add_f32_e32 v0, v40, v0
	v_pk_mul_f32 v[28:29], v[28:29], v[56:57] op_sel_hi:[1,0]
	v_pk_mul_f32 v[30:31], v[26:27], v[26:27]
	v_add_f32_e32 v0, v41, v0
	v_pk_fma_f32 v[28:29], v[32:33], v[54:55], v[28:29] op_sel_hi:[1,0,1] neg_lo:[0,0,1] neg_hi:[0,0,1]
	v_add_f32_e32 v0, v30, v0
	v_pk_mul_f32 v[32:33], v[28:29], v[28:29]
	v_pk_mul_f32 v[58:59], v[58:59], v[56:57] op_sel_hi:[1,0]
	v_add_f32_e32 v0, v31, v0
	v_pk_fma_f32 v[58:59], v[62:63], v[54:55], v[58:59] op_sel_hi:[1,0,1] neg_lo:[0,0,1] neg_hi:[0,0,1]
	v_add_f32_e32 v0, v32, v0
	v_pk_mul_f32 v[60:61], v[60:61], v[56:57] op_sel_hi:[1,0]
	v_pk_mul_f32 v[62:63], v[58:59], v[58:59]
	v_add_f32_e32 v0, v33, v0
	v_pk_fma_f32 v[60:61], v[64:65], v[54:55], v[60:61] op_sel_hi:[1,0,1] neg_lo:[0,0,1] neg_hi:[0,0,1]
	v_add_f32_e32 v0, v62, v0
	v_pk_mul_f32 v[64:65], v[60:61], v[60:61]
	v_pk_mul_f32 v[18:19], v[18:19], v[56:57] op_sel_hi:[1,0]
	v_add_f32_e32 v0, v63, v0
	v_pk_fma_f32 v[18:19], v[22:23], v[54:55], v[18:19] op_sel_hi:[1,0,1] neg_lo:[0,0,1] neg_hi:[0,0,1]
	v_add_f32_e32 v0, v64, v0
	v_pk_mul_f32 v[20:21], v[20:21], v[56:57] op_sel_hi:[1,0]
	v_pk_mul_f32 v[22:23], v[18:19], v[18:19]
	v_add_f32_e32 v0, v65, v0
	v_pk_fma_f32 v[20:21], v[24:25], v[54:55], v[20:21] op_sel_hi:[1,0,1] neg_lo:[0,0,1] neg_hi:[0,0,1]
	v_add_f32_e32 v0, v22, v0
	v_pk_mul_f32 v[24:25], v[20:21], v[20:21]
	v_pk_mul_f32 v[10:11], v[10:11], v[56:57] op_sel_hi:[1,0]
	v_add_f32_e32 v0, v23, v0
	v_pk_fma_f32 v[10:11], v[14:15], v[54:55], v[10:11] op_sel_hi:[1,0,1] neg_lo:[0,0,1] neg_hi:[0,0,1]
	v_add_f32_e32 v0, v24, v0
	v_pk_mul_f32 v[12:13], v[12:13], v[56:57] op_sel_hi:[1,0]
	v_pk_mul_f32 v[14:15], v[10:11], v[10:11]
	v_add_f32_e32 v0, v25, v0
	v_pk_fma_f32 v[12:13], v[16:17], v[54:55], v[12:13] op_sel_hi:[1,0,1] neg_lo:[0,0,1] neg_hi:[0,0,1]
	v_add_f32_e32 v0, v14, v0
	v_pk_mul_f32 v[16:17], v[12:13], v[12:13]
	v_pk_mul_f32 v[2:3], v[2:3], v[56:57] op_sel_hi:[1,0]
	v_add_f32_e32 v0, v15, v0
	v_pk_fma_f32 v[2:3], v[6:7], v[54:55], v[2:3] op_sel_hi:[1,0,1] neg_lo:[0,0,1] neg_hi:[0,0,1]
	v_add_f32_e32 v0, v16, v0
	v_pk_mul_f32 v[4:5], v[4:5], v[56:57] op_sel_hi:[1,0]
	v_pk_mul_f32 v[6:7], v[2:3], v[2:3]
	v_add_f32_e32 v0, v17, v0
	v_pk_fma_f32 v[4:5], v[8:9], v[54:55], v[4:5] op_sel_hi:[1,0,1] neg_lo:[0,0,1] neg_hi:[0,0,1]
	v_add_f32_e32 v0, v6, v0
	v_pk_mul_f32 v[8:9], v[4:5], v[4:5]
	v_add_f32_e32 v0, v7, v0
	v_add_f32_e32 v0, v8, v0
	v_pk_mul_f32 v[66:67], v[52:53], v[52:53]
	v_add_f32_e32 v0, v9, v0
	v_add_f32_e32 v0, v66, v0
	v_pk_mul_f32 v[68:69], v[50:51], v[50:51]
	v_add_f32_e32 v0, v67, v0
	v_add_f32_e32 v0, v68, v0
	v_add_f32_e32 v0, v69, v0
	ds_bpermute_b32 v6, v205, v0
	v_lshl_add_u64 v[42:43], v[70:71], 0, s[4:5]
	s_mov_b32 s4, 0x18800000
	s_waitcnt lgkmcnt(0)
; __device__ __forceinline__ unsigned pk2(float lo, float hi) { f32x2_t v = {lo, hi}; bf16x2_t b = __builtin_convertvector(v, bf16x2_t); return __builtin_bit_cast(unsigned, b); }
; __device__ __forceinline__ void attn_unit(const Args& c, int l, int b, int h, int qb, float lam, float lam_init, LAS unsigned char* lds) {
;     ...
;     const float rstd = rsqrtf(ss * (1.f / 128.f) + 1e-6f) * (1.0f - lam_init);
;     const float* sw = c.in[28 + z_] + l * 128;
;     bf16* orow = ((bf16*)(wsl + WS_MIXED)) + (seq0 + 128 * qb + 16 * w + r) * 2048 + 1024 + h * 128;
; #pragma unroll
;     for (int vb = 0; vb < 8; ++vb) { const int v0 = 16 * vb + 4 * q4; u32x2v o;
;         o.x = pk2(O[0][vb][0] * rstd * sw[v0], O[0][vb][1] * rstd * sw[v0 + 1]); o.y = pk2(O[0][vb][2] * rstd * sw[v0 + 2], O[0][vb][3] * rstd * sw[v0 + 3]);
;         *(u32x2v*)(orow + v0) = o; }
	v_add_f32_e32 v0, v0, v6
	ds_bpermute_b32 v6, v206, v0
	s_waitcnt lgkmcnt(0)
	v_add_f32_e32 v0, v0, v6
	v_fmamk_f32 v0, v0, 0x3c000000, v178
	v_cmp_gt_f32_e32 vcc, s33, v0
	v_mul_f32_e32 v6, 0x4b800000, v0
	s_nop 0
	v_cndmask_b32_e32 v0, v0, v6, vcc
	v_rsq_f32_e32 v0, v0
	s_nop 0
	v_mul_f32_e32 v6, 0x45800000, v0
	v_cndmask_b32_e32 v0, v0, v6, vcc
	v_mul_f32_e32 v0, v201, v0
	v_pk_mul_f32 v[6:7], v[74:75], v[0:1] op_sel_hi:[1,0]
	v_pk_mul_f32 v[8:9], v[48:49], v[0:1] op_sel_hi:[1,0]
	s_waitcnt vmcnt(0)
	v_pk_mul_f32 v[6:7], v[44:45], v[6:7]
	v_pk_mul_f32 v[8:9], v[46:47], v[8:9]
	v_cvt_pk_bf16_f32 v6, v6, v7
	v_cvt_pk_bf16_f32 v7, v8, v9
	v_add_co_u32_e32 v8, vcc, s4, v70
	v_pk_mul_f32 v[14:15], v[34:35], v[0:1] op_sel_hi:[1,0]
	s_nop 0
	v_addc_co_u32_e32 v9, vcc, 0, v71, vcc
	flat_store_dwordx2 v[8:9], v[6:7] offset:2048
	v_pk_mul_f32 v[10:11], v[10:11], v[0:1] op_sel_hi:[1,0]
	v_pk_mul_f32 v[2:3], v[2:3], v[0:1] op_sel_hi:[1,0]
	v_pk_mul_f32 v[4:5], v[4:5], v[0:1] op_sel_hi:[1,0]
	v_pk_mul_f32 v[6:7], v[152:153], v[14:15]
	v_pk_mul_f32 v[14:15], v[36:37], v[0:1] op_sel_hi:[1,0]
	v_cvt_pk_bf16_f32 v6, v6, v7
	v_pk_mul_f32 v[8:9], v[154:155], v[14:15]
	v_pk_mul_f32 v[14:15], v[26:27], v[0:1] op_sel_hi:[1,0]
	v_cvt_pk_bf16_f32 v7, v8, v9
	flat_store_dwordx2 v[42:43], v[6:7] offset:32
	v_pk_mul_f32 v[6:7], v[156:157], v[14:15]
	v_pk_mul_f32 v[14:15], v[28:29], v[0:1] op_sel_hi:[1,0]
	v_cvt_pk_bf16_f32 v6, v6, v7
	v_pk_mul_f32 v[8:9], v[158:159], v[14:15]
	v_pk_mul_f32 v[14:15], v[58:59], v[0:1] op_sel_hi:[1,0]
	v_cvt_pk_bf16_f32 v7, v8, v9
	flat_store_dwordx2 v[42:43], v[6:7] offset:64
	v_pk_mul_f32 v[6:7], v[160:161], v[14:15]
	v_pk_mul_f32 v[14:15], v[60:61], v[0:1] op_sel_hi:[1,0]
	v_cvt_pk_bf16_f32 v6, v6, v7
	v_pk_mul_f32 v[8:9], v[162:163], v[14:15]
	v_pk_mul_f32 v[14:15], v[18:19], v[0:1] op_sel_hi:[1,0]
	v_cvt_pk_bf16_f32 v7, v8, v9
	flat_store_dwordx2 v[42:43], v[6:7] offset:96
	v_pk_mul_f32 v[6:7], v[164:165], v[14:15]
	v_pk_mul_f32 v[14:15], v[20:21], v[0:1] op_sel_hi:[1,0]
	v_cvt_pk_bf16_f32 v6, v6, v7
	v_pk_mul_f32 v[8:9], v[166:167], v[14:15]
	s_nop 0
	v_cvt_pk_bf16_f32 v7, v8, v9
	flat_store_dwordx2 v[42:43], v[6:7] offset:128
	v_pk_mul_f32 v[6:7], v[168:169], v[10:11]
	v_pk_mul_f32 v[10:11], v[12:13], v[0:1] op_sel_hi:[1,0]
	v_cvt_pk_bf16_f32 v6, v6, v7
	v_pk_mul_f32 v[8:9], v[170:171], v[10:11]
	s_nop 0
	v_cvt_pk_bf16_f32 v7, v8, v9
	flat_store_dwordx2 v[42:43], v[6:7] offset:160
	v_pk_mul_f32 v[2:3], v[172:173], v[2:3]
	v_pk_mul_f32 v[4:5], v[174:175], v[4:5]
	v_cvt_pk_bf16_f32 v2, v2, v3
	v_cvt_pk_bf16_f32 v3, v4, v5
	flat_store_dwordx2 v[42:43], v[2:3] offset:192
	v_pk_mul_f32 v[6:7], v[52:53], v[0:1] op_sel_hi:[1,0]
	s_mov_b64 s[2:3], 0
	v_pk_mul_f32 v[2:3], v[180:181], v[6:7]
	v_pk_mul_f32 v[6:7], v[50:51], v[0:1] op_sel_hi:[1,0]
	v_cvt_pk_bf16_f32 v2, v2, v3
	v_pk_mul_f32 v[4:5], v[182:183], v[6:7]
	s_nop 0
	v_cvt_pk_bf16_f32 v3, v4, v5
	flat_store_dwordx2 v[42:43], v[2:3] offset:224

; __device__ __forceinline__ void unpack8(u32x4v w, float* f) { f[0] = bflo(w.x); f[1] = bfhi(w.x); f[2] = bflo(w.y); f[3] = bfhi(w.y); f[4] = bflo(w.z); f[5] = bfhi(w.z); f[6] = bflo(w.w); f[7] = bfhi(w.w); }
; __device__ __forceinline__ void attn_unit(const Args& c, int l, int b, int h, int qb, float lam, float lam_init, LAS unsigned char* lds) {
;     ...
;         for (int hh = 0; hh < 2; ++hh) {
;             const int kr = skey + 64 * hh;
;             float f[16]; unpack8(gk0[hh], f); unpack8(gk1[hh], f + 8);
;             float kw[16];
; #pragma unroll
;             for (int e4 = 0; e4 < 4; ++e4) { const f32x4 t4 = ((const f32x4*)kwp)[e4]; kw[4 * e4] = t4.x; kw[4 * e4 + 1] = t4.y; kw[4 * e4 + 2] = t4.z; kw[4 * e4 + 3] = t4.w; }
;             float ss = 0.f;
; #pragma unroll
;             for (int e = 0; e < 16; ++e) ss += f[e] * f[e];
;             ss += __shfl_xor(ss, 1); ss += __shfl_xor(ss, 2);
;             const float sc = rsqrtf(ss * (1.f / 64.f) + 1e-6f);
;             u32x4v o;
.LBB0_245:
	s_waitcnt lgkmcnt(0)
	s_barrier
	global_load_dwordx4 v[114:117], v[188:189], off offset:48
	global_load_dwordx4 v[118:121], v[188:189], off offset:32
	global_load_dwordx4 v[122:125], v[188:189], off offset:16
	global_load_dwordx4 v[126:129], v[188:189], off
	s_waitcnt vmcnt(4)
	v_and_b32_e32 v145, 0xffff0000, v66
	v_and_b32_e32 v171, 0xffff0000, v90
	v_lshlrev_b32_e32 v144, 16, v66
	v_lshlrev_b32_e32 v170, 16, v90
	v_mov_b32_e32 v230, v171
	v_mov_b32_e32 v231, v145
	v_lshlrev_b32_e32 v142, 16, v67
	v_lshlrev_b32_e32 v168, 16, v91
	v_mov_b32_e32 v228, v170
	v_mov_b32_e32 v229, v144
	v_pk_mul_f32 v[230:231], v[230:231], v[230:231]
	v_and_b32_e32 v143, 0xffff0000, v67
	v_and_b32_e32 v169, 0xffff0000, v91
	v_mov_b32_e32 v224, v168
	v_mov_b32_e32 v225, v142
	v_pk_fma_f32 v[228:229], v[228:229], v[228:229], v[230:231]
	v_lshlrev_b32_e32 v140, 16, v68
	v_lshlrev_b32_e32 v166, 16, v92
	v_mov_b32_e32 v226, v169
	v_mov_b32_e32 v227, v143
	v_pk_fma_f32 v[224:225], v[224:225], v[224:225], v[228:229]
	v_and_b32_e32 v141, 0xffff0000, v68
	v_and_b32_e32 v167, 0xffff0000, v92
	v_mov_b32_e32 v220, v166
	v_mov_b32_e32 v221, v140
	v_pk_fma_f32 v[224:225], v[226:227], v[226:227], v[224:225]
	v_lshlrev_b32_e32 v138, 16, v69
	v_lshlrev_b32_e32 v164, 16, v93
	v_mov_b32_e32 v222, v167
	v_mov_b32_e32 v223, v141
	v_pk_fma_f32 v[220:221], v[220:221], v[220:221], v[224:225]
	v_and_b32_e32 v139, 0xffff0000, v69
	v_lshlrev_b32_e32 v152, 16, v70
	v_and_b32_e32 v153, 0xffff0000, v70
	v_and_b32_e32 v165, 0xffff0000, v93
	v_lshlrev_b32_e32 v176, 16, v94
	v_and_b32_e32 v177, 0xffff0000, v94
	v_mov_b32_e32 v182, v164
	v_mov_b32_e32 v183, v138
	v_pk_fma_f32 v[220:221], v[222:223], v[222:223], v[220:221]
	v_pk_mul_f32 v[154:155], v[152:153], v[152:153]
	v_pk_mul_f32 v[180:181], v[176:177], v[176:177]
	v_mov_b32_e32 v218, v165
	v_mov_b32_e32 v219, v139
	v_pk_fma_f32 v[182:183], v[182:183], v[182:183], v[220:221]
	v_lshlrev_b32_e32 v146, 16, v71
	v_and_b32_e32 v147, 0xffff0000, v71
	v_lshlrev_b32_e32 v172, 16, v95
	v_and_b32_e32 v173, 0xffff0000, v95
	v_pk_fma_f32 v[182:183], v[218:219], v[218:219], v[182:183]
	v_mov_b32_e32 v218, v180
	v_mov_b32_e32 v219, v154
	v_pk_mul_f32 v[150:151], v[146:147], v[146:147]
	v_pk_mul_f32 v[174:175], v[172:173], v[172:173]
	v_pk_add_f32 v[182:183], v[218:219], v[182:183]
	v_mov_b32_e32 v154, v181
	v_and_b32_e32 v134, 0xffff0000, v72
	v_lshlrev_b32_e32 v135, 16, v72
	v_and_b32_e32 v156, 0xffff0000, v96
	v_lshlrev_b32_e32 v157, 16, v96
	v_pk_add_f32 v[154:155], v[154:155], v[182:183]
	v_mov_b32_e32 v180, v174
	v_mov_b32_e32 v181, v150
	v_pk_mul_f32 v[130:131], v[134:135], v[134:135]
	v_pk_mul_f32 v[158:159], v[156:157], v[156:157]
	v_pk_add_f32 v[154:155], v[180:181], v[154:155]
	v_mov_b32_e32 v150, v175
	v_and_b32_e32 v136, 0xffff0000, v73
	v_lshlrev_b32_e32 v137, 16, v73
	v_and_b32_e32 v160, 0xffff0000, v97
	v_lshlrev_b32_e32 v161, 16, v97
	v_pk_add_f32 v[150:151], v[150:151], v[154:155]
	v_mov_b32_e32 v154, v159
	v_mov_b32_e32 v155, v131
	v_pk_mul_f32 v[132:133], v[136:137], v[136:137]
	v_pk_mul_f32 v[162:163], v[160:161], v[160:161]
	v_pk_add_f32 v[150:151], v[154:155], v[150:151]
	v_mov_b32_e32 v159, v130
	v_pk_add_f32 v[130:131], v[158:159], v[150:151]
	v_mov_b32_e32 v150, v163
	v_mov_b32_e32 v151, v133
	v_pk_add_f32 v[130:131], v[150:151], v[130:131]
	v_mov_b32_e32 v163, v132
	v_pk_add_f32 v[130:131], v[162:163], v[130:131]
	ds_bpermute_b32 v133, v203, v131
	ds_bpermute_b32 v132, v203, v130
	ds_write_b128 v211, v[78:81] offset:34816
	ds_write_b128 v211, v[82:85] offset:34832
	s_cmp_ge_u32 s35, s22
	s_waitcnt lgkmcnt(2)
	v_pk_add_f32 v[130:131], v[130:131], v[132:133]
	ds_bpermute_b32 v133, v204, v131
	ds_bpermute_b32 v132, v204, v130
	s_waitcnt lgkmcnt(0)
	v_pk_add_f32 v[130:131], v[130:131], v[132:133]
	s_nop 0
	v_pk_fma_f32 v[150:151], v[130:131], s[26:27], v[178:179] op_sel_hi:[1,0,0]
	s_nop 0
	v_mul_f32_e32 v130, 0x4b800000, v151
	v_cmp_gt_f32_e32 vcc, s33, v151
	s_nop 1
	v_cndmask_b32_e32 v130, v151, v130, vcc
	v_rsq_f32_e32 v130, v130
	s_nop 0
	v_mul_f32_e32 v131, 0x45800000, v130
	v_cndmask_b32_e32 v154, v130, v131, vcc
	v_pk_mul_f32 v[130:131], v[154:155], v[144:145] op_sel_hi:[0,1]
	v_pk_mul_f32 v[132:133], v[154:155], v[142:143] op_sel_hi:[0,1]
	s_waitcnt vmcnt(0)
; #define LAS __attribute__((address_space(3)))
; __device__ __forceinline__ unsigned pk2(float lo, float hi) { f32x2_t v = {lo, hi}; bf16x2_t b = __builtin_convertvector(v, bf16x2_t); return __builtin_bit_cast(unsigned, b); }
; #define ATT_FETCH(KT) do { _Pragma("unroll") for (int hh = 0; hh < 2; ++hh) { const bf16* krow = P + (seq0 + 128 * (KT) + 64 * hh + skey) * PW; \
;         gk0[hh] = *(const u32x4v*)(krow + KC + part * 16); gk1[hh] = *(const u32x4v*)(krow + KC + part * 16 + 8); \
;         gv0[hh] = *(const u32x4v*)(krow + VC + part * 16); gv1[hh] = *(const u32x4v*)(krow + VC + part * 16 + 8); } } while (0)
; __device__ __forceinline__ void attn_unit(const Args& c, int l, int b, int h, int qb, float lam, float lam_init, LAS unsigned char* lds) {
;     ...
;             u32x4v o;
;             o.x = pk2(f[0] * sc * kw[0], f[1] * sc * kw[1]); o.y = pk2(f[2] * sc * kw[2], f[3] * sc * kw[3]); o.z = pk2(f[4] * sc * kw[4], f[5] * sc * kw[5]); o.w = pk2(f[6] * sc * kw[6], f[7] * sc * kw[7]);
;             *(LAS u32x4v*)(Kt + kr * 136 + part * 16) = o;
;             o.x = pk2(f[8] * sc * kw[8], f[9] * sc * kw[9]); o.y = pk2(f[10] * sc * kw[10], f[11] * sc * kw[11]); o.z = pk2(f[12] * sc * kw[12], f[13] * sc * kw[13]); o.w = pk2(f[14] * sc * kw[14], f[15] * sc * kw[15]);
;             *(LAS u32x4v*)(Kt + kr * 136 + part * 16 + 8) = o;
;             *(LAS u32x4v*)(Vs + kr * 136 + part * 16) = gv0[hh]; *(LAS u32x4v*)(Vs + kr * 136 + part * 16 + 8) = gv1[hh];
;         }
;         if (kt + 1 < NT) ATT_FETCH(kt + 1);
	v_pk_mul_f32 v[130:131], v[126:127], v[130:131]
	v_pk_mul_f32 v[132:133], v[128:129], v[132:133]
	v_cvt_pk_bf16_f32 v130, v130, v131
	v_cvt_pk_bf16_f32 v131, v132, v133
	v_pk_mul_f32 v[132:133], v[154:155], v[140:141] op_sel_hi:[0,1]
	v_pk_mul_f32 v[138:139], v[154:155], v[138:139] op_sel_hi:[0,1]
	v_pk_mul_f32 v[132:133], v[122:123], v[132:133]
	v_pk_mul_f32 v[138:139], v[124:125], v[138:139]
	v_cvt_pk_bf16_f32 v132, v132, v133
	v_cvt_pk_bf16_f32 v133, v138, v139
	ds_write_b128 v211, v[130:133]
	v_pk_mul_f32 v[130:131], v[154:155], v[152:153] op_sel_hi:[0,1]
	v_pk_mul_f32 v[132:133], v[154:155], v[146:147] op_sel_hi:[0,1]
	v_pk_mul_f32 v[130:131], v[118:119], v[130:131]
	v_pk_mul_f32 v[132:133], v[120:121], v[132:133]
	v_cvt_pk_bf16_f32 v130, v130, v131
	v_cvt_pk_bf16_f32 v131, v132, v133
	v_pk_mul_f32 v[132:133], v[154:155], v[134:135] op_sel_hi:[0,1]
	v_pk_mul_f32 v[132:133], v[114:115], v[132:133] op_sel:[0,1] op_sel_hi:[1,0]
	v_cmp_gt_f32_e32 vcc, s33, v150
	v_cvt_pk_bf16_f32 v132, v132, v133
	v_mul_f32_e32 v133, 0x4b800000, v150
	v_cndmask_b32_e32 v133, v150, v133, vcc
	v_pk_mul_f32 v[134:135], v[154:155], v[136:137] op_sel_hi:[0,1]
	v_rsq_f32_e32 v136, v133
	v_pk_mul_f32 v[134:135], v[116:117], v[134:135] op_sel:[0,1] op_sel_hi:[1,0]
	s_nop 0
	v_cvt_pk_bf16_f32 v133, v134, v135
	ds_write_b128 v211, v[130:133] offset:16
	v_mul_f32_e32 v130, 0x45800000, v136
	v_cndmask_b32_e32 v130, v136, v130, vcc
	v_pk_mul_f32 v[132:133], v[130:131], v[170:171] op_sel_hi:[0,1]
	v_pk_mul_f32 v[126:127], v[126:127], v[132:133]
	v_pk_mul_f32 v[132:133], v[130:131], v[168:169] op_sel_hi:[0,1]
	v_pk_mul_f32 v[128:129], v[128:129], v[132:133]
	v_cvt_pk_bf16_f32 v126, v126, v127
	v_cvt_pk_bf16_f32 v127, v128, v129
	v_pk_mul_f32 v[128:129], v[130:131], v[166:167] op_sel_hi:[0,1]
	v_pk_mul_f32 v[122:123], v[122:123], v[128:129]
	s_nop 0
	v_cvt_pk_bf16_f32 v128, v122, v123
	v_pk_mul_f32 v[122:123], v[130:131], v[164:165] op_sel_hi:[0,1]
	v_pk_mul_f32 v[122:123], v[124:125], v[122:123]
	s_nop 0
	v_cvt_pk_bf16_f32 v129, v122, v123
	v_pk_mul_f32 v[122:123], v[130:131], v[176:177] op_sel_hi:[0,1]
	v_pk_mul_f32 v[118:119], v[118:119], v[122:123]
	v_pk_mul_f32 v[122:123], v[130:131], v[172:173] op_sel_hi:[0,1]
	v_pk_mul_f32 v[120:121], v[120:121], v[122:123]
	v_cvt_pk_bf16_f32 v118, v118, v119
	v_cvt_pk_bf16_f32 v119, v120, v121
	v_pk_mul_f32 v[120:121], v[130:131], v[156:157] op_sel_hi:[0,1]
	v_pk_mul_f32 v[114:115], v[114:115], v[120:121] op_sel:[0,1] op_sel_hi:[1,0]
	ds_write_b128 v211, v[126:129] offset:17408
	v_cvt_pk_bf16_f32 v120, v114, v115
	v_pk_mul_f32 v[114:115], v[130:131], v[160:161] op_sel_hi:[0,1]
	v_pk_mul_f32 v[114:115], v[116:117], v[114:115] op_sel:[0,1] op_sel_hi:[1,0]
	s_nop 0
	v_cvt_pk_bf16_f32 v121, v114, v115
	ds_write_b128 v211, v[118:121] offset:17424
	ds_write_b128 v211, v[98:101] offset:52224
	ds_write_b128 v211, v[102:105] offset:52240
	s_cbranch_scc1 .LBB0_247
	s_add_i32 s8, s18, s5
	s_add_i32 s14, s8, 0x80
	v_lshl_add_u64 v[66:67], s[14:15], 0, v[186:187]
	s_add_i32 s14, s8, 0xc0
	v_mov_b64_e32 v[90:91], s[2:3]
	v_lshl_add_u64 v[92:93], s[14:15], 0, v[186:187]
	v_mad_u64_u32 v[78:79], s[6:7], v66, s27, v[90:91]
	v_mad_u64_u32 v[98:99], s[6:7], v92, s27, v[90:91]
	v_mad_i32_i24 v79, v67, s27, v79
	s_mov_b32 s21, s15
	s_mov_b32 s29, s15
	v_mad_i32_i24 v99, v93, s27, v99
	v_lshl_add_u64 v[66:67], v[78:79], 0, s[20:21]
	v_lshl_add_u64 v[78:79], v[78:79], 0, s[28:29]
	v_lshl_add_u64 v[90:91], v[98:99], 0, s[20:21]
	v_lshl_add_u64 v[98:99], v[98:99], 0, s[28:29]
	v_lshl_add_u64 v[70:71], v[66:67], 0, v[0:1]
	v_lshl_add_u64 v[82:83], v[78:79], 0, v[0:1]
	v_lshl_add_u64 v[94:95], v[90:91], 0, v[0:1]
	v_lshl_add_u64 v[102:103], v[98:99], 0, v[0:1]
	global_load_dwordx4 v[66:69], v[70:71], off
	s_nop 0
	global_load_dwordx4 v[70:73], v[70:71], off offset:16
	s_nop 0
	global_load_dwordx4 v[78:81], v[82:83], off
	s_nop 0
	global_load_dwordx4 v[82:85], v[82:83], off offset:16
	s_nop 0
	global_load_dwordx4 v[90:93], v[94:95], off
	s_nop 0
	global_load_dwordx4 v[94:97], v[94:95], off offset:16
	s_nop 0
	global_load_dwordx4 v[98:101], v[102:103], off
	s_nop 0
	global_load_dwordx4 v[102:105], v[102:103], off offset:16
